# rope factor from integer ops (no SGPR mask); Up epilogue: 16th conv-weight load issued before its wait
# baseline (speedup 1.0000x reference)
.LBB0_247:
	s_lshl_b32 s0, s16, 8
	v_readlane_b32 s1, v253, 37
	s_or_b32 s0, s0, s1
	v_lshlrev_b32_e32 v152, 3, v160
	v_add_u32_e32 v150, s0, v152
	s_cmp_gt_i32 s16, 7
	s_mov_b64 s[18:19], -1
	s_cbranch_scc1 .LBB0_269
	s_add_i32 s0, s16, -4
	s_cmp_lt_u32 s0, 2
	s_cselect_b64 s[18:19], -1, 0
	s_cmp_gt_u32 s0, 1
	s_cbranch_scc0 .LBB0_269
	s_cmp_gt_i32 s16, 3
	s_mov_b64 s[0:1], -1
	s_cbranch_scc0 .LBB0_267
	s_cmp_eq_u32 s16, 6
	s_cselect_b64 vcc, -1, 0
	v_readlane_b32 s44, v251, 49
	s_and_b64 s[0:1], vcc, exec
	v_readlane_b32 s50, v251, 55
	v_readlane_b32 s52, v251, 57
	v_readlane_b32 s51, v251, 56
	v_readlane_b32 s53, v251, 58
	s_cselect_b32 s1, s50, s52
	v_lshlrev_b32_e32 v136, 2, v160
	s_cselect_b32 s0, s51, s53
	s_add_u32 s22, s1, s6
	v_or_b32_e32 v130, 1, v136
	s_addc_u32 s23, s0, s7
	v_add_u32_e32 v131, 9, v136
	v_cmp_gt_i32_e64 s[0:1], 8, v130
	v_or_b32_e32 v132, 2, v136
	v_add_u32_e32 v128, 8, v136
	v_cmp_gt_i32_e64 s[42:43], 2, v160
	v_cndmask_b32_e64 v130, v131, v130, s[0:1]
	v_add_u32_e32 v133, 10, v136
	v_cmp_gt_i32_e64 s[0:1], 8, v132
	v_or_b32_e32 v134, 3, v136
	v_cndmask_b32_e64 v128, v128, v136, s[42:43]
	v_cndmask_b32_e64 v132, v133, v132, s[0:1]
	v_add_u32_e32 v135, 11, v136
	v_cmp_gt_i32_e64 s[0:1], 8, v134
	v_ashrrev_i32_e32 v129, 31, v128
	v_lshl_add_u64 v[128:129], v[128:129], 2, s[22:23]
	v_cndmask_b32_e64 v134, v135, v134, s[0:1]
	v_ashrrev_i32_e32 v131, 31, v130
	v_ashrrev_i32_e32 v133, 31, v132
	v_ashrrev_i32_e32 v135, 31, v134
	v_lshl_add_u64 v[130:131], v[130:131], 2, s[22:23]
	v_lshl_add_u64 v[132:133], v[132:133], 2, s[22:23]
	v_lshl_add_u64 v[134:135], v[134:135], 2, s[22:23]
	global_load_dword v174, v[128:129], off
	global_load_dword v159, v[130:131], off
	global_load_dword v156, v[132:133], off
	global_load_dword v155, v[134:135], off
	global_load_dword v157, v[134:135], off offset:32
	global_load_dword v154, v[132:133], off offset:32
	global_load_dword v175, v[130:131], off offset:32
	global_load_dword v158, v[128:129], off offset:32
	s_cmp_lt_i32 s20, 64
	v_and_b32_e32 v129, 4, v136
	s_cselect_b64 s[22:23], -1, 0
	s_cmp_gt_i32 s20, 63
	v_and_b32_e32 v189, 63, v185
	v_mov_b32_e32 v178, 0
	v_mov_b32_e32 v128, 1.0
	v_lshlrev_b32_e32 v153, 3, v129
	v_mov_b32_e32 v134, 1.0
	v_mov_b32_e32 v180, 0
	v_mov_b32_e32 v181, 1.0
	v_mov_b32_e32 v135, 0
	v_mov_b32_e32 v130, 1.0
	v_mov_b32_e32 v136, 0
	v_mov_b32_e32 v137, 1.0
	v_mov_b32_e32 v131, 0
	v_readlane_b32 s45, v251, 50
	v_readlane_b32 s46, v251, 51
	v_readlane_b32 s47, v251, 52
	v_readlane_b32 s48, v251, 53
	v_readlane_b32 s49, v251, 54
	v_readlane_b32 s54, v251, 59
	v_readlane_b32 s55, v251, 60
	v_readlane_b32 s56, v251, 61
	v_readlane_b32 s57, v251, 62
	v_readlane_b32 s58, v251, 63
	v_readlane_b32 s59, v252, 0
	s_cbranch_scc1 .LBB0_252
	v_bfe_u32 v129, v184, 6, 7
	v_cndmask_b32_e64 v129, v189, v129, s[42:43]
	v_cvt_f32_u32_e32 v132, v129
	v_lshrrev_b32_e32 v133, 5, v153
	v_sub_u32_e32 v133, 0, v133
	v_and_b32_e32 v133, 0x35c28f6, v133
	v_sub_u32_e32 v133, 0x3f800000, v133
	v_mul_f32_e32 v132, v132, v133
	v_mul_f32_e32 v135, 0x3e22f983, v132
	v_cos_f32_e32 v134, v135
	v_sin_f32_e32 v135, v135
	v_mul_f32_e32 v137, 0x3d4e2601, v132
	v_cos_f32_e32 v136, v137
	v_sin_f32_e32 v137, v137
	v_mul_f32_e32 v131, 0x3c826136, v132
	v_cos_f32_e32 v130, v131
	v_sin_f32_e32 v131, v131
	v_mul_f32_e32 v133, 0x3ba4eb34, v132
	v_cos_f32_e32 v132, v133
	v_sin_f32_e32 v133, v133
	s_nop 0
	s_waitcnt vmcnt(0)
	v_mov_b32_e32 v180, v135
	v_mov_b32_e32 v181, v136
	v_mov_b32_e32 v135, v137
	v_mov_b32_e32 v136, v131
	v_mov_b32_e32 v137, v132
	v_mov_b32_e32 v131, v133
.LBB0_252:
	v_pk_mul_f32 v[132:133], v[126:127], v[126:127]
	v_pk_mul_f32 v[162:163], v[124:125], v[124:125]
	v_readlane_b32 s0, v252, 52
	v_pk_mov_b32 v[164:165], v[162:163], v[132:133] op_sel:[1,0]
	v_mov_b32_e32 v163, v133
	v_pk_add_f32 v[132:133], v[164:165], v[162:163]
	v_pk_mul_f32 v[162:163], v[122:123], v[122:123]
	v_pk_mul_f32 v[164:165], v[120:121], v[120:121]
	v_mov_b32_e32 v166, v162
	v_mov_b32_e32 v167, v164
	v_mov_b32_e32 v164, v163
	v_pk_add_f32 v[162:163], v[166:167], v[164:165]
	v_add_f32_e32 v129, v132, v133
	v_mbcnt_lo_u32_b32 v132, -1, 0
	v_mbcnt_hi_u32_b32 v132, -1, v132
	v_add_f32_e32 v129, v129, v163
	v_lshlrev_b32_e32 v132, 2, v132
	v_add_f32_e32 v129, v162, v129
	v_xor_b32_e32 v132, 64, v132
	ds_bpermute_b32 v132, v132, v129
	v_readlane_b32 s1, v252, 53
	v_ashrrev_i32_e32 v151, 31, v150
	v_mov_b32_e32 v194, v180
	v_mov_b32_e32 v195, v135
	s_waitcnt lgkmcnt(0)
	v_add_f32_e32 v129, v129, v132
	v_mbcnt_lo_u32_b32 v132, -1, 0
	v_mbcnt_hi_u32_b32 v132, -1, v132
	v_mov_b32_e32 v172, v134
	v_lshlrev_b32_e32 v132, 2, v132
	v_xor_b32_e32 v132, 0x80, v132
	ds_bpermute_b32 v162, v132, v129
	v_mov_b32_e32 v132, 0x3e8293ee
	v_cndmask_b32_e32 v176, 1.0, v132, vcc
	v_mov_b64_e32 v[132:133], s[0:1]
	v_mad_i64_i32 v[132:133], s[0:1], v184, s71, v[132:133]
	s_waitcnt lgkmcnt(0)
	v_add_f32_e32 v129, v129, v162
	v_fmamk_f32 v129, v129, 0x3d000000, v208
	v_rsq_f32_e32 v162, v129
	v_lshl_add_u64 v[164:165], v[150:151], 1, v[132:133]
	v_mov_b32_e32 v173, v181
	v_mov_b32_e32 v198, v136
	v_pk_mul_f32 v[132:133], v[126:127], v[162:163] op_sel_hi:[1,0]
	v_pk_mul_f32 v[166:167], v[124:125], v[162:163] op_sel_hi:[1,0]
	v_pk_mul_f32 v[168:169], v[122:123], v[162:163] op_sel_hi:[1,0]
	v_pk_mul_f32 v[162:163], v[120:121], v[162:163] op_sel_hi:[1,0]
	v_mov_b32_e32 v170, v166
	v_mov_b32_e32 v171, v163
	v_mov_b32_e32 v163, v167
	s_waitcnt vmcnt(0)
	v_pk_mul_f32 v[162:163], v[158:159], v[162:163]
	v_pk_mul_f32 v[170:171], v[174:175], v[170:171]
	v_pk_mul_f32 v[166:167], v[134:135], v[162:163]
	v_mov_b32_e32 v186, v170
	v_pk_fma_f32 v[166:167], v[180:181], v[170:171], v[166:167]
	v_mov_b32_e32 v187, v163
	v_mov_b32_e32 v163, v171
	v_mov_b32_e32 v170, v132
	v_mov_b32_e32 v171, v169
	v_mov_b32_e32 v169, v133
	v_pk_mul_f32 v[162:163], v[194:195], v[162:163]
	v_pk_mul_f32 v[170:171], v[156:157], v[170:171]
	v_pk_mul_f32 v[132:133], v[154:155], v[168:169]
	v_pk_fma_f32 v[162:163], v[172:173], v[186:187], v[162:163] neg_lo:[0,0,1] neg_hi:[0,0,1]
	v_pk_mul_f32 v[168:169], v[130:131], v[132:133]
	v_mov_b32_e32 v187, v133
	v_mov_b32_e32 v199, v131
	v_mov_b32_e32 v133, v171
	v_mov_b32_e32 v196, v130
	v_mov_b32_e32 v197, v137
	v_mov_b32_e32 v186, v170
	v_pk_mul_f32 v[132:133], v[198:199], v[132:133]
	v_pk_mul_f32 v[162:163], v[176:177], v[162:163] op_sel_hi:[0,1]
	v_pk_fma_f32 v[132:133], v[196:197], v[186:187], v[132:133] neg_lo:[0,0,1] neg_hi:[0,0,1]
	v_pk_mul_f32 v[166:167], v[176:177], v[166:167] op_sel_hi:[0,1]
	v_pk_mul_f32 v[132:133], v[176:177], v[132:133] op_sel_hi:[0,1]
	v_cvt_pk_bf16_f32 v190, v162, v163
	v_cvt_pk_bf16_f32 v191, v132, v133
	v_pk_mul_f32 v[132:133], v[118:119], v[118:119]
	v_pk_mul_f32 v[162:163], v[116:117], v[116:117]
	v_pk_fma_f32 v[168:169], v[136:137], v[170:171], v[168:169]
	v_cvt_pk_bf16_f32 v192, v166, v167
	v_pk_mov_b32 v[166:167], v[162:163], v[132:133] op_sel:[1,0]
	v_mov_b32_e32 v163, v133
	v_pk_mul_f32 v[168:169], v[176:177], v[168:169] op_sel_hi:[0,1]
	v_pk_add_f32 v[132:133], v[166:167], v[162:163]
	v_pk_mul_f32 v[162:163], v[114:115], v[114:115]
	v_pk_mul_f32 v[166:167], v[112:113], v[112:113]
	v_cvt_pk_bf16_f32 v193, v168, v169
	v_mov_b32_e32 v168, v162
	v_mov_b32_e32 v169, v166
	v_mov_b32_e32 v166, v163
	global_store_dwordx4 v[164:165], v[190:193], off
	v_pk_add_f32 v[162:163], v[168:169], v[166:167]
	v_add_f32_e32 v129, v132, v133
	v_mbcnt_lo_u32_b32 v132, -1, 0
	v_mbcnt_hi_u32_b32 v132, -1, v132
	v_add_f32_e32 v129, v129, v163
	v_lshlrev_b32_e32 v132, 2, v132
	v_add_f32_e32 v129, v162, v129
	v_xor_b32_e32 v132, 64, v132
	ds_bpermute_b32 v132, v132, v129
	s_andn2_b64 vcc, exec, s[22:23]
	v_mov_b32_e32 v179, 1.0
	s_waitcnt lgkmcnt(0)
	v_add_f32_e32 v129, v129, v132
	v_mbcnt_lo_u32_b32 v132, -1, 0
	v_mbcnt_hi_u32_b32 v132, -1, v132
	s_nop 0
	v_lshlrev_b32_e32 v132, 2, v132
	v_xor_b32_e32 v132, 0x80, v132
	ds_bpermute_b32 v132, v132, v129
	s_waitcnt lgkmcnt(0)
	v_add_f32_e32 v129, v129, v132
	v_fmamk_f32 v129, v129, 0x3d000000, v208
	v_rsq_f32_e32 v132, v129
	v_add_u32_e32 v129, 16, v185
	v_and_b32_e32 v186, 63, v129
	v_cndmask_b32_e64 v129, 0, 1, s[22:23]
	v_pk_mul_f32 v[162:163], v[118:119], v[132:133] op_sel_hi:[1,0]
	v_pk_mul_f32 v[166:167], v[116:117], v[132:133] op_sel_hi:[1,0]
	v_pk_mul_f32 v[168:169], v[114:115], v[132:133] op_sel_hi:[1,0]
	v_pk_mul_f32 v[132:133], v[112:113], v[132:133] op_sel_hi:[1,0]
	v_mov_b32_e32 v170, v166
	v_mov_b32_e32 v171, v133
	v_mov_b32_e32 v133, v167
	v_pk_mul_f32 v[170:171], v[174:175], v[170:171]
	v_pk_mul_f32 v[132:133], v[158:159], v[132:133]
	v_mov_b32_e32 v166, v170
	v_pk_mul_f32 v[134:135], v[134:135], v[132:133]
	v_mov_b32_e32 v167, v133
	v_mov_b32_e32 v133, v171
	v_pk_mul_f32 v[132:133], v[194:195], v[132:133]
	v_pk_fma_f32 v[134:135], v[180:181], v[170:171], v[134:135]
	v_pk_fma_f32 v[132:133], v[172:173], v[166:167], v[132:133] neg_lo:[0,0,1] neg_hi:[0,0,1]
	v_mov_b32_e32 v167, v169
	v_mov_b32_e32 v169, v163
	v_mov_b32_e32 v166, v162
	v_pk_mul_f32 v[162:163], v[154:155], v[168:169]
	v_pk_mul_f32 v[166:167], v[156:157], v[166:167]
	v_pk_mul_f32 v[130:131], v[130:131], v[162:163]
	v_pk_mul_f32 v[134:135], v[176:177], v[134:135] op_sel_hi:[0,1]
	v_pk_fma_f32 v[130:131], v[136:137], v[166:167], v[130:131]
	v_pk_mul_f32 v[132:133], v[176:177], v[132:133] op_sel_hi:[0,1]
	v_pk_mul_f32 v[136:137], v[176:177], v[130:131] op_sel_hi:[0,1]
	v_mov_b32_e32 v131, v163
	v_mov_b32_e32 v163, v167
	v_mov_b32_e32 v130, v166
	v_pk_mul_f32 v[162:163], v[198:199], v[162:163]
	v_cmp_ne_u32_e64 s[0:1], 1, v129
	v_pk_fma_f32 v[130:131], v[196:197], v[130:131], v[162:163] neg_lo:[0,0,1] neg_hi:[0,0,1]
	v_mov_b32_e32 v129, 0
	v_pk_mul_f32 v[162:163], v[176:177], v[130:131] op_sel_hi:[0,1]
	v_cvt_pk_bf16_f32 v130, v132, v133
	v_cvt_pk_bf16_f32 v131, v162, v163
	v_cvt_pk_bf16_f32 v132, v134, v135
	v_cvt_pk_bf16_f32 v133, v136, v137
	global_store_dwordx4 v[164:165], v[130:133], off offset:64
	v_add_u32_e32 v136, 16, v184
	s_nop 0
	v_mov_b32_e32 v132, 1.0
	v_mov_b32_e32 v130, 0
	v_mov_b32_e32 v131, 1.0
	v_mov_b32_e32 v133, 0
	s_cbranch_vccnz .LBB0_254
	v_bfe_u32 v128, v136, 6, 7
	v_cndmask_b32_e64 v128, v186, v128, s[42:43]
	v_cvt_f32_u32_e32 v134, v128
	v_lshrrev_b32_e32 v135, 5, v153
	v_sub_u32_e32 v135, 0, v135
	v_and_b32_e32 v135, 0x35c28f6, v135
	v_sub_u32_e32 v135, 0x3f800000, v135
	v_mul_f32_e32 v134, v134, v135
	v_mul_f32_e32 v129, 0x3e22f983, v134
	v_cos_f32_e32 v128, v129
	v_sin_f32_e32 v129, v129
	v_mul_f32_e32 v131, 0x3d4e2601, v134
	v_cos_f32_e32 v130, v131
	v_sin_f32_e32 v131, v131
	v_mul_f32_e32 v133, 0x3c826136, v134
	v_cos_f32_e32 v132, v133
	v_sin_f32_e32 v133, v133
	v_mul_f32_e32 v135, 0x3ba4eb34, v134
	v_cos_f32_e32 v134, v135
	v_sin_f32_e32 v135, v135
	s_nop 0
	v_mov_b32_e32 v178, v129
	v_mov_b32_e32 v179, v130
	v_mov_b32_e32 v129, v131
	v_mov_b32_e32 v130, v133
	v_mov_b32_e32 v131, v134
	v_mov_b32_e32 v133, v135
.LBB0_254:
	v_pk_mul_f32 v[134:135], v[110:111], v[110:111]
	v_pk_mul_f32 v[162:163], v[108:109], v[108:109]
	v_readlane_b32 s22, v252, 52
	v_pk_mov_b32 v[164:165], v[162:163], v[134:135] op_sel:[1,0]
	v_mov_b32_e32 v163, v135
	v_pk_add_f32 v[134:135], v[164:165], v[162:163]
	v_pk_mul_f32 v[162:163], v[106:107], v[106:107]
	v_pk_mul_f32 v[164:165], v[104:105], v[104:105]
	v_mov_b32_e32 v166, v162
	v_mov_b32_e32 v167, v164
	v_mov_b32_e32 v164, v163
	v_pk_add_f32 v[162:163], v[166:167], v[164:165]
	v_add_f32_e32 v134, v134, v135
	v_mbcnt_lo_u32_b32 v135, -1, 0
	v_mbcnt_hi_u32_b32 v135, -1, v135
	v_add_f32_e32 v134, v134, v163
	v_lshlrev_b32_e32 v135, 2, v135
	v_add_f32_e32 v134, v162, v134
	v_xor_b32_e32 v135, 64, v135
	ds_bpermute_b32 v135, v135, v134
	v_readlane_b32 s23, v252, 53
	v_mov_b32_e32 v180, v178
	v_mov_b32_e32 v181, v129
	v_mov_b32_e32 v170, v128
	s_waitcnt lgkmcnt(0)
	v_add_f32_e32 v137, v134, v135
	v_mbcnt_lo_u32_b32 v134, -1, 0
	v_mbcnt_hi_u32_b32 v134, -1, v134
	v_mov_b32_e32 v171, v179
	v_lshlrev_b32_e32 v134, 2, v134
	v_xor_b32_e32 v134, 0x80, v134
	ds_bpermute_b32 v162, v134, v137
	v_mov_b64_e32 v[134:135], s[22:23]
	v_mad_i64_i32 v[134:135], s[22:23], v136, s71, v[134:135]
	v_lshl_add_u64 v[164:165], v[150:151], 1, v[134:135]
	s_waitcnt lgkmcnt(0)
	v_add_f32_e32 v137, v137, v162
	v_fmamk_f32 v137, v137, 0x3d000000, v208
	v_rsq_f32_e32 v162, v137
	v_mov_b32_e32 v192, v130
	v_mov_b32_e32 v193, v133
	v_mov_b32_e32 v177, v176
	v_pk_mul_f32 v[134:135], v[110:111], v[162:163] op_sel_hi:[1,0]
	v_pk_mul_f32 v[136:137], v[108:109], v[162:163] op_sel_hi:[1,0]
	v_pk_mul_f32 v[166:167], v[106:107], v[162:163] op_sel_hi:[1,0]
	v_pk_mul_f32 v[162:163], v[104:105], v[162:163] op_sel_hi:[1,0]
	v_mov_b32_e32 v168, v136
	v_mov_b32_e32 v169, v163
	v_mov_b32_e32 v163, v137
	v_pk_mul_f32 v[136:137], v[158:159], v[162:163]
	v_pk_mul_f32 v[168:169], v[174:175], v[168:169]
	v_pk_mul_f32 v[162:163], v[128:129], v[136:137]
	v_mov_b32_e32 v172, v168
	v_pk_fma_f32 v[162:163], v[178:179], v[168:169], v[162:163]
	v_mov_b32_e32 v173, v137
	v_mov_b32_e32 v137, v169
	v_mov_b32_e32 v168, v134
	v_mov_b32_e32 v169, v167
	v_mov_b32_e32 v167, v135
	v_pk_mul_f32 v[168:169], v[156:157], v[168:169]
	v_pk_mul_f32 v[134:135], v[154:155], v[166:167]
	v_pk_mul_f32 v[136:137], v[180:181], v[136:137]
	v_pk_mul_f32 v[166:167], v[132:133], v[134:135]
	v_mov_b32_e32 v191, v135
	v_mov_b32_e32 v135, v169
	v_pk_fma_f32 v[136:137], v[170:171], v[172:173], v[136:137] neg_lo:[0,0,1] neg_hi:[0,0,1]
	v_mov_b32_e32 v172, v132
	v_mov_b32_e32 v173, v131
	v_mov_b32_e32 v190, v168
	v_pk_mul_f32 v[134:135], v[192:193], v[134:135]
	v_pk_fma_f32 v[166:167], v[130:131], v[168:169], v[166:167]
	v_pk_fma_f32 v[134:135], v[172:173], v[190:191], v[134:135] neg_lo:[0,0,1] neg_hi:[0,0,1]
	v_pk_mul_f32 v[162:163], v[176:177], v[162:163]
	v_pk_mul_f32 v[136:137], v[176:177], v[136:137]
	v_pk_mul_f32 v[166:167], v[176:177], v[166:167]
	v_pk_mul_f32 v[168:169], v[176:177], v[134:135]
	v_cvt_pk_bf16_f32 v134, v136, v137
	v_cvt_pk_bf16_f32 v135, v168, v169
	v_cvt_pk_bf16_f32 v136, v162, v163
	v_cvt_pk_bf16_f32 v137, v166, v167
	global_store_dwordx4 v[164:165], v[134:137], off
	v_xor_b32_e32 v187, 32, v189
	s_and_b64 vcc, exec, s[0:1]
	v_pk_mul_f32 v[134:135], v[102:103], v[102:103]
	v_pk_mul_f32 v[136:137], v[100:101], v[100:101]
	s_nop 0
	v_pk_mov_b32 v[162:163], v[136:137], v[134:135] op_sel:[1,0]
	v_mov_b32_e32 v137, v135
	v_pk_add_f32 v[134:135], v[162:163], v[136:137]
	v_pk_mul_f32 v[136:137], v[98:99], v[98:99]
	v_pk_mul_f32 v[162:163], v[96:97], v[96:97]
	v_mov_b32_e32 v166, v136
	v_mov_b32_e32 v167, v162
	v_mov_b32_e32 v162, v137
	v_pk_add_f32 v[136:137], v[166:167], v[162:163]
	v_add_f32_e32 v134, v134, v135
	v_mbcnt_lo_u32_b32 v135, -1, 0
	v_mbcnt_hi_u32_b32 v135, -1, v135
	v_add_f32_e32 v134, v134, v137
	v_lshlrev_b32_e32 v135, 2, v135
	v_add_f32_e32 v134, v136, v134
	v_xor_b32_e32 v135, 64, v135
	ds_bpermute_b32 v135, v135, v134
	s_waitcnt lgkmcnt(0)
	v_add_f32_e32 v134, v134, v135
	v_mbcnt_lo_u32_b32 v135, -1, 0
	v_mbcnt_hi_u32_b32 v135, -1, v135
	s_nop 0
	v_lshlrev_b32_e32 v135, 2, v135
	v_xor_b32_e32 v135, 0x80, v135
	ds_bpermute_b32 v135, v135, v134
	s_waitcnt lgkmcnt(0)
	v_add_f32_e32 v134, v134, v135
	v_fmamk_f32 v134, v134, 0x3d000000, v208
	v_rsq_f32_e32 v134, v134
	s_nop 0
	v_pk_mul_f32 v[136:137], v[102:103], v[134:135] op_sel_hi:[1,0]
	v_pk_mul_f32 v[162:163], v[100:101], v[134:135] op_sel_hi:[1,0]
	v_pk_mul_f32 v[166:167], v[98:99], v[134:135] op_sel_hi:[1,0]
	v_pk_mul_f32 v[134:135], v[96:97], v[134:135] op_sel_hi:[1,0]
	v_mov_b32_e32 v168, v162
	v_mov_b32_e32 v169, v135
	v_mov_b32_e32 v135, v163
	v_pk_mul_f32 v[134:135], v[158:159], v[134:135]
	v_pk_mul_f32 v[168:169], v[174:175], v[168:169]
	v_pk_mul_f32 v[128:129], v[128:129], v[134:135]
	s_nop 0
	v_pk_fma_f32 v[128:129], v[178:179], v[168:169], v[128:129]
	v_mov_b32_e32 v178, 0
	v_pk_mul_f32 v[162:163], v[176:177], v[128:129]
	v_mov_b32_e32 v129, v135
	v_mov_b32_e32 v135, v169
	v_mov_b32_e32 v128, v168
	v_pk_mul_f32 v[134:135], v[180:181], v[134:135]
	v_mov_b32_e32 v180, 0
	v_pk_fma_f32 v[128:129], v[170:171], v[128:129], v[134:135] neg_lo:[0,0,1] neg_hi:[0,0,1]
	v_mov_b32_e32 v135, v167
	v_mov_b32_e32 v167, v137
	v_mov_b32_e32 v134, v136
	v_pk_mul_f32 v[136:137], v[154:155], v[166:167]
	v_pk_mul_f32 v[134:135], v[156:157], v[134:135]
	v_pk_mul_f32 v[132:133], v[132:133], v[136:137]
	v_pk_mul_f32 v[128:129], v[176:177], v[128:129]
	v_pk_fma_f32 v[130:131], v[130:131], v[134:135], v[132:133]
	v_cvt_pk_bf16_f32 v128, v128, v129
	v_pk_mul_f32 v[132:133], v[176:177], v[130:131]
	v_mov_b32_e32 v131, v137
	v_mov_b32_e32 v137, v135
	v_mov_b32_e32 v130, v134
	v_pk_mul_f32 v[134:135], v[192:193], v[136:137]
	v_mov_b32_e32 v181, 1.0
	v_pk_fma_f32 v[130:131], v[172:173], v[130:131], v[134:135] neg_lo:[0,0,1] neg_hi:[0,0,1]
	v_mov_b32_e32 v134, 1.0
	v_pk_mul_f32 v[130:131], v[176:177], v[130:131]
	v_mov_b32_e32 v135, 0
	v_cvt_pk_bf16_f32 v129, v130, v131
	v_cvt_pk_bf16_f32 v130, v162, v163
	v_cvt_pk_bf16_f32 v131, v132, v133
	global_store_dwordx4 v[164:165], v[128:131], off offset:64
	v_mov_b32_e32 v136, 0
	v_mov_b32_e32 v137, 1.0
	v_add_u32_e32 v129, 32, v184
	v_mov_b32_e32 v128, 1.0
	v_mov_b32_e32 v130, 1.0
	v_mov_b32_e32 v131, 0
	s_cbranch_vccnz .LBB0_256
	v_bfe_u32 v130, v129, 6, 7
	v_cndmask_b32_e64 v130, v187, v130, s[42:43]
	v_cvt_f32_u32_e32 v132, v130
	v_lshrrev_b32_e32 v133, 5, v153
	v_sub_u32_e32 v133, 0, v133
	v_and_b32_e32 v133, 0x35c28f6, v133
	v_sub_u32_e32 v133, 0x3f800000, v133
	v_mul_f32_e32 v132, v132, v133
	v_mul_f32_e32 v135, 0x3e22f983, v132
	v_cos_f32_e32 v134, v135
	v_sin_f32_e32 v135, v135
	v_mul_f32_e32 v137, 0x3d4e2601, v132
	v_cos_f32_e32 v136, v137
	v_sin_f32_e32 v137, v137
	v_mul_f32_e32 v131, 0x3c826136, v132
	v_cos_f32_e32 v130, v131
	v_sin_f32_e32 v131, v131
	v_mul_f32_e32 v133, 0x3ba4eb34, v132
	v_cos_f32_e32 v132, v133
	v_sin_f32_e32 v133, v133
	s_nop 0
	v_mov_b32_e32 v180, v135
	v_mov_b32_e32 v181, v136
	v_mov_b32_e32 v135, v137
	v_mov_b32_e32 v136, v131
	v_mov_b32_e32 v137, v132
	v_mov_b32_e32 v131, v133
.LBB0_256:
	v_pk_mul_f32 v[132:133], v[94:95], v[94:95]
	v_pk_mul_f32 v[162:163], v[92:93], v[92:93]
	v_readlane_b32 s22, v252, 52
	v_pk_mov_b32 v[164:165], v[162:163], v[132:133] op_sel:[1,0]
	v_mov_b32_e32 v163, v133
	v_pk_add_f32 v[132:133], v[164:165], v[162:163]
	v_pk_mul_f32 v[162:163], v[90:91], v[90:91]
	v_pk_mul_f32 v[164:165], v[88:89], v[88:89]
	v_mov_b32_e32 v166, v162
	v_mov_b32_e32 v167, v164
	v_mov_b32_e32 v164, v163
	v_pk_add_f32 v[162:163], v[166:167], v[164:165]
	v_add_f32_e32 v132, v132, v133
	v_mbcnt_lo_u32_b32 v133, -1, 0
	v_mbcnt_hi_u32_b32 v133, -1, v133
	v_add_f32_e32 v132, v132, v163
	v_lshlrev_b32_e32 v133, 2, v133
	v_add_f32_e32 v132, v162, v132
	v_xor_b32_e32 v133, 64, v133
	ds_bpermute_b32 v133, v133, v132
	v_readlane_b32 s23, v252, 53
	v_mov_b32_e32 v194, v180
	v_mov_b32_e32 v195, v135
	v_mov_b32_e32 v172, v134
	s_waitcnt lgkmcnt(0)
	v_add_f32_e32 v162, v132, v133
	v_mbcnt_lo_u32_b32 v132, -1, 0
	v_mbcnt_hi_u32_b32 v132, -1, v132
	v_mov_b32_e32 v173, v181
	v_lshlrev_b32_e32 v132, 2, v132
	v_xor_b32_e32 v132, 0x80, v132
	ds_bpermute_b32 v163, v132, v162
	v_mov_b64_e32 v[132:133], s[22:23]
	v_mad_i64_i32 v[132:133], s[22:23], v129, s71, v[132:133]
	v_lshl_add_u64 v[164:165], v[150:151], 1, v[132:133]
	s_waitcnt lgkmcnt(0)
	v_add_f32_e32 v162, v162, v163
	v_fmamk_f32 v162, v162, 0x3d000000, v208
	v_rsq_f32_e32 v162, v162
	v_mov_b32_e32 v198, v136
	v_mov_b32_e32 v199, v131
	v_mov_b32_e32 v196, v130
	v_pk_mul_f32 v[132:133], v[94:95], v[162:163] op_sel_hi:[1,0]
	v_pk_mul_f32 v[166:167], v[92:93], v[162:163] op_sel_hi:[1,0]
	v_pk_mul_f32 v[168:169], v[90:91], v[162:163] op_sel_hi:[1,0]
	v_pk_mul_f32 v[162:163], v[88:89], v[162:163] op_sel_hi:[1,0]
	v_mov_b32_e32 v170, v166
	v_mov_b32_e32 v171, v163
	v_mov_b32_e32 v163, v167
	v_pk_mul_f32 v[162:163], v[158:159], v[162:163]
	v_pk_mul_f32 v[170:171], v[174:175], v[170:171]
	v_pk_mul_f32 v[166:167], v[134:135], v[162:163]
	v_mov_b32_e32 v190, v170
	v_pk_fma_f32 v[166:167], v[180:181], v[170:171], v[166:167]
	v_mov_b32_e32 v191, v163
	v_mov_b32_e32 v163, v171
	v_mov_b32_e32 v170, v132
	v_mov_b32_e32 v171, v169
	v_mov_b32_e32 v169, v133
	v_pk_mul_f32 v[162:163], v[194:195], v[162:163]
	v_pk_mul_f32 v[170:171], v[156:157], v[170:171]
	v_pk_mul_f32 v[132:133], v[154:155], v[168:169]
	v_pk_fma_f32 v[162:163], v[172:173], v[190:191], v[162:163] neg_lo:[0,0,1] neg_hi:[0,0,1]
	v_pk_mul_f32 v[168:169], v[130:131], v[132:133]
	v_mov_b32_e32 v191, v133
	v_mov_b32_e32 v133, v171
	v_mov_b32_e32 v197, v137
	v_mov_b32_e32 v190, v170
	v_pk_mul_f32 v[132:133], v[198:199], v[132:133]
	v_pk_mul_f32 v[162:163], v[176:177], v[162:163]
	v_pk_fma_f32 v[132:133], v[196:197], v[190:191], v[132:133] neg_lo:[0,0,1] neg_hi:[0,0,1]
	v_pk_mul_f32 v[166:167], v[176:177], v[166:167]
	v_pk_mul_f32 v[132:133], v[176:177], v[132:133]
	v_cvt_pk_bf16_f32 v190, v162, v163
	v_cvt_pk_bf16_f32 v191, v132, v133
	v_pk_mul_f32 v[132:133], v[86:87], v[86:87]
	v_pk_mul_f32 v[162:163], v[84:85], v[84:85]
	v_pk_fma_f32 v[168:169], v[136:137], v[170:171], v[168:169]
	v_cvt_pk_bf16_f32 v192, v166, v167
	v_pk_mov_b32 v[166:167], v[162:163], v[132:133] op_sel:[1,0]
	v_mov_b32_e32 v163, v133
	v_pk_mul_f32 v[168:169], v[176:177], v[168:169]
	v_pk_add_f32 v[132:133], v[166:167], v[162:163]
	v_pk_mul_f32 v[162:163], v[82:83], v[82:83]
	v_pk_mul_f32 v[166:167], v[80:81], v[80:81]
	v_cvt_pk_bf16_f32 v193, v168, v169
	v_mov_b32_e32 v168, v162
	v_mov_b32_e32 v169, v166
	v_mov_b32_e32 v166, v163
	global_store_dwordx4 v[164:165], v[190:193], off
	v_pk_add_f32 v[162:163], v[168:169], v[166:167]
	v_add_f32_e32 v129, v132, v133
	v_mbcnt_lo_u32_b32 v132, -1, 0
	v_mbcnt_hi_u32_b32 v132, -1, v132
	v_add_f32_e32 v129, v129, v163
	v_lshlrev_b32_e32 v132, 2, v132
	v_add_f32_e32 v129, v162, v129
	v_xor_b32_e32 v132, 64, v132
	ds_bpermute_b32 v132, v132, v129
	s_and_b64 vcc, exec, s[0:1]
	v_mov_b32_e32 v179, 1.0
	s_waitcnt lgkmcnt(0)
	v_add_f32_e32 v129, v129, v132
	v_mbcnt_lo_u32_b32 v132, -1, 0
	v_mbcnt_hi_u32_b32 v132, -1, v132
	s_nop 0
	v_lshlrev_b32_e32 v132, 2, v132
	v_xor_b32_e32 v132, 0x80, v132
	ds_bpermute_b32 v132, v132, v129
	s_waitcnt lgkmcnt(0)
	v_add_f32_e32 v129, v129, v132
	v_fmamk_f32 v129, v129, 0x3d000000, v208
	v_rsq_f32_e32 v132, v129
	v_add_u32_e32 v129, 48, v185
	v_and_b32_e32 v188, 63, v129
	v_mov_b32_e32 v129, 0
	v_pk_mul_f32 v[162:163], v[86:87], v[132:133] op_sel_hi:[1,0]
	v_pk_mul_f32 v[166:167], v[84:85], v[132:133] op_sel_hi:[1,0]
	v_pk_mul_f32 v[168:169], v[82:83], v[132:133] op_sel_hi:[1,0]
	v_pk_mul_f32 v[132:133], v[80:81], v[132:133] op_sel_hi:[1,0]
	v_mov_b32_e32 v170, v166
	v_mov_b32_e32 v171, v133
	v_mov_b32_e32 v133, v167
	v_pk_mul_f32 v[170:171], v[174:175], v[170:171]
	v_pk_mul_f32 v[132:133], v[158:159], v[132:133]
	v_mov_b32_e32 v166, v170
	v_pk_mul_f32 v[134:135], v[134:135], v[132:133]
	v_mov_b32_e32 v167, v133
	v_mov_b32_e32 v133, v171
	v_pk_mul_f32 v[132:133], v[194:195], v[132:133]
	v_pk_fma_f32 v[134:135], v[180:181], v[170:171], v[134:135]
	v_pk_fma_f32 v[132:133], v[172:173], v[166:167], v[132:133] neg_lo:[0,0,1] neg_hi:[0,0,1]
	v_mov_b32_e32 v167, v169
	v_mov_b32_e32 v169, v163
	v_mov_b32_e32 v166, v162
	v_pk_mul_f32 v[162:163], v[154:155], v[168:169]
	v_pk_mul_f32 v[166:167], v[156:157], v[166:167]
	v_pk_mul_f32 v[130:131], v[130:131], v[162:163]
	v_pk_mul_f32 v[134:135], v[176:177], v[134:135]
	v_pk_fma_f32 v[130:131], v[136:137], v[166:167], v[130:131]
	v_pk_mul_f32 v[132:133], v[176:177], v[132:133]
	v_pk_mul_f32 v[136:137], v[176:177], v[130:131]
	v_mov_b32_e32 v131, v163
	v_mov_b32_e32 v163, v167
	v_mov_b32_e32 v130, v166
	v_pk_mul_f32 v[162:163], v[198:199], v[162:163]
	s_nop 0
	v_pk_fma_f32 v[130:131], v[196:197], v[130:131], v[162:163] neg_lo:[0,0,1] neg_hi:[0,0,1]
	s_nop 0
	v_pk_mul_f32 v[162:163], v[176:177], v[130:131]
	v_cvt_pk_bf16_f32 v130, v132, v133
	v_cvt_pk_bf16_f32 v131, v162, v163
	v_cvt_pk_bf16_f32 v132, v134, v135
	v_cvt_pk_bf16_f32 v133, v136, v137
	global_store_dwordx4 v[164:165], v[130:133], off offset:64
	v_add_u32_e32 v136, 48, v184
	s_nop 0
	v_mov_b32_e32 v132, 1.0
	v_mov_b32_e32 v130, 0
	v_mov_b32_e32 v131, 1.0
	v_mov_b32_e32 v133, 0
	s_cbranch_vccnz .LBB0_258
	v_bfe_u32 v128, v136, 6, 7
	v_cndmask_b32_e64 v128, v188, v128, s[42:43]
	v_cvt_f32_u32_e32 v134, v128
	v_lshrrev_b32_e32 v135, 5, v153
	v_sub_u32_e32 v135, 0, v135
	v_and_b32_e32 v135, 0x35c28f6, v135
	v_sub_u32_e32 v135, 0x3f800000, v135
	v_mul_f32_e32 v134, v134, v135
	v_mul_f32_e32 v129, 0x3e22f983, v134
	v_cos_f32_e32 v128, v129
	v_sin_f32_e32 v129, v129
	v_mul_f32_e32 v131, 0x3d4e2601, v134
	v_cos_f32_e32 v130, v131
	v_sin_f32_e32 v131, v131
	v_mul_f32_e32 v133, 0x3c826136, v134
	v_cos_f32_e32 v132, v133
	v_sin_f32_e32 v133, v133
	v_mul_f32_e32 v135, 0x3ba4eb34, v134
	v_cos_f32_e32 v134, v135
	v_sin_f32_e32 v135, v135
	s_nop 0
	v_mov_b32_e32 v178, v129
	v_mov_b32_e32 v179, v130
	v_mov_b32_e32 v129, v131
	v_mov_b32_e32 v130, v133
	v_mov_b32_e32 v131, v134
	v_mov_b32_e32 v133, v135
.LBB0_258:
	v_pk_mul_f32 v[134:135], v[78:79], v[78:79]
	v_pk_mul_f32 v[162:163], v[76:77], v[76:77]
	v_readlane_b32 s22, v252, 52
	v_pk_mov_b32 v[164:165], v[162:163], v[134:135] op_sel:[1,0]
	v_mov_b32_e32 v163, v135
	v_pk_add_f32 v[134:135], v[164:165], v[162:163]
	v_pk_mul_f32 v[162:163], v[74:75], v[74:75]
	v_pk_mul_f32 v[164:165], v[72:73], v[72:73]
	v_mov_b32_e32 v166, v162
	v_mov_b32_e32 v167, v164
	v_mov_b32_e32 v164, v163
	v_pk_add_f32 v[162:163], v[166:167], v[164:165]
	v_add_f32_e32 v134, v134, v135
	v_mbcnt_lo_u32_b32 v135, -1, 0
	v_mbcnt_hi_u32_b32 v135, -1, v135
	v_add_f32_e32 v134, v134, v163
	v_lshlrev_b32_e32 v135, 2, v135
	v_add_f32_e32 v134, v162, v134
	v_xor_b32_e32 v135, 64, v135
	ds_bpermute_b32 v135, v135, v134
	v_readlane_b32 s23, v252, 53
	v_mov_b32_e32 v180, v178
	v_mov_b32_e32 v181, v129
	v_mov_b32_e32 v170, v128
	s_waitcnt lgkmcnt(0)
	v_add_f32_e32 v137, v134, v135
	v_mbcnt_lo_u32_b32 v134, -1, 0
	v_mbcnt_hi_u32_b32 v134, -1, v134
	v_mov_b32_e32 v171, v179
	v_lshlrev_b32_e32 v134, 2, v134
	v_xor_b32_e32 v134, 0x80, v134
	ds_bpermute_b32 v162, v134, v137
	v_mov_b64_e32 v[134:135], s[22:23]
	v_mad_i64_i32 v[134:135], s[22:23], v136, s71, v[134:135]
	v_lshl_add_u64 v[164:165], v[150:151], 1, v[134:135]
	s_waitcnt lgkmcnt(0)
	v_add_f32_e32 v137, v137, v162
	v_fmamk_f32 v137, v137, 0x3d000000, v208
	v_rsq_f32_e32 v162, v137
	v_mov_b32_e32 v192, v130
	v_mov_b32_e32 v193, v133
	s_and_b64 vcc, exec, s[0:1]
	v_pk_mul_f32 v[134:135], v[78:79], v[162:163] op_sel_hi:[1,0]
	v_pk_mul_f32 v[136:137], v[76:77], v[162:163] op_sel_hi:[1,0]
	v_pk_mul_f32 v[166:167], v[74:75], v[162:163] op_sel_hi:[1,0]
	v_pk_mul_f32 v[162:163], v[72:73], v[162:163] op_sel_hi:[1,0]
	v_mov_b32_e32 v168, v136
	v_mov_b32_e32 v169, v163
	v_mov_b32_e32 v163, v137
	v_pk_mul_f32 v[136:137], v[158:159], v[162:163]
	v_pk_mul_f32 v[168:169], v[174:175], v[168:169]
	v_pk_mul_f32 v[162:163], v[128:129], v[136:137]
	v_mov_b32_e32 v172, v168
	v_pk_fma_f32 v[162:163], v[178:179], v[168:169], v[162:163]
	v_mov_b32_e32 v173, v137
	v_mov_b32_e32 v137, v169
	v_mov_b32_e32 v168, v134
	v_mov_b32_e32 v169, v167
	v_mov_b32_e32 v167, v135
	v_pk_mul_f32 v[168:169], v[156:157], v[168:169]
	v_pk_mul_f32 v[134:135], v[154:155], v[166:167]
	v_pk_mul_f32 v[136:137], v[180:181], v[136:137]
	v_pk_mul_f32 v[166:167], v[132:133], v[134:135]
	v_mov_b32_e32 v191, v135
	v_mov_b32_e32 v135, v169
	v_pk_fma_f32 v[136:137], v[170:171], v[172:173], v[136:137] neg_lo:[0,0,1] neg_hi:[0,0,1]
	v_mov_b32_e32 v172, v132
	v_mov_b32_e32 v173, v131
	v_mov_b32_e32 v190, v168
	v_pk_mul_f32 v[134:135], v[192:193], v[134:135]
	v_pk_fma_f32 v[166:167], v[130:131], v[168:169], v[166:167]
	v_pk_fma_f32 v[134:135], v[172:173], v[190:191], v[134:135] neg_lo:[0,0,1] neg_hi:[0,0,1]
	v_pk_mul_f32 v[162:163], v[176:177], v[162:163]
	v_pk_mul_f32 v[136:137], v[176:177], v[136:137]
	v_pk_mul_f32 v[166:167], v[176:177], v[166:167]
	v_pk_mul_f32 v[168:169], v[176:177], v[134:135]
	v_cvt_pk_bf16_f32 v134, v136, v137
	v_cvt_pk_bf16_f32 v135, v168, v169
	v_cvt_pk_bf16_f32 v136, v162, v163
	v_cvt_pk_bf16_f32 v137, v166, v167
	global_store_dwordx4 v[164:165], v[134:137], off
	s_nop 1
	v_pk_mul_f32 v[134:135], v[70:71], v[70:71]
	v_pk_mul_f32 v[136:137], v[68:69], v[68:69]
	s_nop 0
	v_pk_mov_b32 v[162:163], v[136:137], v[134:135] op_sel:[1,0]
	v_mov_b32_e32 v137, v135
	v_pk_add_f32 v[134:135], v[162:163], v[136:137]
	v_pk_mul_f32 v[136:137], v[66:67], v[66:67]
	v_pk_mul_f32 v[162:163], v[64:65], v[64:65]
	v_mov_b32_e32 v166, v136
	v_mov_b32_e32 v167, v162
	v_mov_b32_e32 v162, v137
	v_pk_add_f32 v[136:137], v[166:167], v[162:163]
	v_add_f32_e32 v134, v134, v135
	v_mbcnt_lo_u32_b32 v135, -1, 0
	v_mbcnt_hi_u32_b32 v135, -1, v135
	v_add_f32_e32 v134, v134, v137
	v_lshlrev_b32_e32 v135, 2, v135
	v_add_f32_e32 v134, v136, v134
	v_xor_b32_e32 v135, 64, v135
	ds_bpermute_b32 v135, v135, v134
	s_waitcnt lgkmcnt(0)
	v_add_f32_e32 v134, v134, v135
	v_mbcnt_lo_u32_b32 v135, -1, 0
	v_mbcnt_hi_u32_b32 v135, -1, v135
	s_nop 0
	v_lshlrev_b32_e32 v135, 2, v135
	v_xor_b32_e32 v135, 0x80, v135
	ds_bpermute_b32 v135, v135, v134
	s_waitcnt lgkmcnt(0)
	v_add_f32_e32 v134, v134, v135
	v_fmamk_f32 v134, v134, 0x3d000000, v208
	v_rsq_f32_e32 v134, v134
	s_nop 0
	v_pk_mul_f32 v[136:137], v[70:71], v[134:135] op_sel_hi:[1,0]
	v_pk_mul_f32 v[162:163], v[68:69], v[134:135] op_sel_hi:[1,0]
	v_pk_mul_f32 v[166:167], v[66:67], v[134:135] op_sel_hi:[1,0]
	v_pk_mul_f32 v[134:135], v[64:65], v[134:135] op_sel_hi:[1,0]
	v_mov_b32_e32 v168, v162
	v_mov_b32_e32 v169, v135
	v_mov_b32_e32 v135, v163
	v_pk_mul_f32 v[134:135], v[158:159], v[134:135]
	v_pk_mul_f32 v[168:169], v[174:175], v[168:169]
	v_pk_mul_f32 v[128:129], v[128:129], v[134:135]
	s_nop 0
	v_pk_fma_f32 v[128:129], v[178:179], v[168:169], v[128:129]
	v_mov_b32_e32 v178, 0
	v_pk_mul_f32 v[162:163], v[176:177], v[128:129]
	v_mov_b32_e32 v129, v135
	v_mov_b32_e32 v135, v169
	v_mov_b32_e32 v128, v168
	v_pk_mul_f32 v[134:135], v[180:181], v[134:135]
	v_mov_b32_e32 v180, 0
	v_pk_fma_f32 v[128:129], v[170:171], v[128:129], v[134:135] neg_lo:[0,0,1] neg_hi:[0,0,1]
	v_mov_b32_e32 v135, v167
	v_mov_b32_e32 v167, v137
	v_mov_b32_e32 v134, v136
	v_pk_mul_f32 v[136:137], v[154:155], v[166:167]
	v_pk_mul_f32 v[134:135], v[156:157], v[134:135]
	v_pk_mul_f32 v[132:133], v[132:133], v[136:137]
	v_pk_mul_f32 v[128:129], v[176:177], v[128:129]
	v_pk_fma_f32 v[130:131], v[130:131], v[134:135], v[132:133]
	v_cvt_pk_bf16_f32 v128, v128, v129
	v_pk_mul_f32 v[132:133], v[176:177], v[130:131]
	v_mov_b32_e32 v131, v137
	v_mov_b32_e32 v137, v135
	v_mov_b32_e32 v130, v134
	v_pk_mul_f32 v[134:135], v[192:193], v[136:137]
	v_mov_b32_e32 v181, 1.0
	v_pk_fma_f32 v[130:131], v[172:173], v[130:131], v[134:135] neg_lo:[0,0,1] neg_hi:[0,0,1]
	v_mov_b32_e32 v134, 1.0
	v_pk_mul_f32 v[130:131], v[176:177], v[130:131]
	v_mov_b32_e32 v135, 0
	v_cvt_pk_bf16_f32 v129, v130, v131
	v_cvt_pk_bf16_f32 v130, v162, v163
	v_cvt_pk_bf16_f32 v131, v132, v133
	global_store_dwordx4 v[164:165], v[128:131], off offset:64
	v_mov_b32_e32 v136, 0
	v_mov_b32_e32 v137, 1.0
	v_add_u32_e32 v129, 0x80, v184
	v_mov_b32_e32 v128, 1.0
	v_mov_b32_e32 v130, 1.0
	v_mov_b32_e32 v131, 0
	s_cbranch_vccnz .LBB0_260
	v_bfe_u32 v130, v129, 6, 7
	v_cndmask_b32_e64 v130, v189, v130, s[42:43]
	v_cvt_f32_u32_e32 v132, v130
	v_lshrrev_b32_e32 v133, 5, v153
	v_sub_u32_e32 v133, 0, v133
	v_and_b32_e32 v133, 0x35c28f6, v133
	v_sub_u32_e32 v133, 0x3f800000, v133
	v_mul_f32_e32 v132, v132, v133
	v_mul_f32_e32 v135, 0x3e22f983, v132
	v_cos_f32_e32 v134, v135
	v_sin_f32_e32 v135, v135
	v_mul_f32_e32 v137, 0x3d4e2601, v132
	v_cos_f32_e32 v136, v137
	v_sin_f32_e32 v137, v137
	v_mul_f32_e32 v131, 0x3c826136, v132
	v_cos_f32_e32 v130, v131
	v_sin_f32_e32 v131, v131
	v_mul_f32_e32 v133, 0x3ba4eb34, v132
	v_cos_f32_e32 v132, v133
	v_sin_f32_e32 v133, v133
	s_nop 0
	v_mov_b32_e32 v180, v135
	v_mov_b32_e32 v181, v136
	v_mov_b32_e32 v135, v137
	v_mov_b32_e32 v136, v131
	v_mov_b32_e32 v137, v132
	v_mov_b32_e32 v131, v133
.LBB0_260:
	v_pk_mul_f32 v[132:133], v[62:63], v[62:63]
	v_pk_mul_f32 v[162:163], v[60:61], v[60:61]
	v_readlane_b32 s22, v252, 52
	v_pk_mov_b32 v[164:165], v[162:163], v[132:133] op_sel:[1,0]
	v_mov_b32_e32 v163, v133
	v_pk_add_f32 v[132:133], v[164:165], v[162:163]
	v_pk_mul_f32 v[162:163], v[58:59], v[58:59]
	v_pk_mul_f32 v[164:165], v[56:57], v[56:57]
	v_mov_b32_e32 v166, v162
	v_mov_b32_e32 v167, v164
	v_mov_b32_e32 v164, v163
	v_pk_add_f32 v[162:163], v[166:167], v[164:165]
	v_add_f32_e32 v132, v132, v133
	v_mbcnt_lo_u32_b32 v133, -1, 0
	v_mbcnt_hi_u32_b32 v133, -1, v133
	v_add_f32_e32 v132, v132, v163
	v_lshlrev_b32_e32 v133, 2, v133
	v_add_f32_e32 v132, v162, v132
	v_xor_b32_e32 v133, 64, v133
	ds_bpermute_b32 v133, v133, v132
	v_readlane_b32 s23, v252, 53
	v_mov_b32_e32 v194, v180
	v_mov_b32_e32 v195, v135
	v_mov_b32_e32 v172, v134
	s_waitcnt lgkmcnt(0)
	v_add_f32_e32 v162, v132, v133
	v_mbcnt_lo_u32_b32 v132, -1, 0
	v_mbcnt_hi_u32_b32 v132, -1, v132
	v_mov_b32_e32 v173, v181
	v_lshlrev_b32_e32 v132, 2, v132
	v_xor_b32_e32 v132, 0x80, v132
	ds_bpermute_b32 v163, v132, v162
	v_mov_b64_e32 v[132:133], s[22:23]
	v_mad_i64_i32 v[132:133], s[22:23], v129, s71, v[132:133]
	v_lshl_add_u64 v[164:165], v[150:151], 1, v[132:133]
	s_waitcnt lgkmcnt(0)
	v_add_f32_e32 v162, v162, v163
	v_fmamk_f32 v162, v162, 0x3d000000, v208
	v_rsq_f32_e32 v162, v162
	v_mov_b32_e32 v198, v136
	v_mov_b32_e32 v199, v131
	v_mov_b32_e32 v196, v130
	v_pk_mul_f32 v[132:133], v[62:63], v[162:163] op_sel_hi:[1,0]
	v_pk_mul_f32 v[166:167], v[60:61], v[162:163] op_sel_hi:[1,0]
	v_pk_mul_f32 v[168:169], v[58:59], v[162:163] op_sel_hi:[1,0]
	v_pk_mul_f32 v[162:163], v[56:57], v[162:163] op_sel_hi:[1,0]
	v_mov_b32_e32 v170, v166
	v_mov_b32_e32 v171, v163
	v_mov_b32_e32 v163, v167
	v_pk_mul_f32 v[162:163], v[158:159], v[162:163]
	v_pk_mul_f32 v[170:171], v[174:175], v[170:171]
	v_pk_mul_f32 v[166:167], v[134:135], v[162:163]
	v_mov_b32_e32 v190, v170
	v_pk_fma_f32 v[166:167], v[180:181], v[170:171], v[166:167]
	v_mov_b32_e32 v191, v163
	v_mov_b32_e32 v163, v171
	v_mov_b32_e32 v170, v132
	v_mov_b32_e32 v171, v169
	v_mov_b32_e32 v169, v133
	v_pk_mul_f32 v[162:163], v[194:195], v[162:163]
	v_pk_mul_f32 v[170:171], v[156:157], v[170:171]
	v_pk_mul_f32 v[132:133], v[154:155], v[168:169]
	v_pk_fma_f32 v[162:163], v[172:173], v[190:191], v[162:163] neg_lo:[0,0,1] neg_hi:[0,0,1]
	v_pk_mul_f32 v[168:169], v[130:131], v[132:133]
	v_mov_b32_e32 v191, v133
	v_mov_b32_e32 v133, v171
	v_mov_b32_e32 v197, v137
	v_mov_b32_e32 v190, v170
	v_pk_mul_f32 v[132:133], v[198:199], v[132:133]
	v_pk_mul_f32 v[162:163], v[176:177], v[162:163]
	v_pk_fma_f32 v[132:133], v[196:197], v[190:191], v[132:133] neg_lo:[0,0,1] neg_hi:[0,0,1]
	v_pk_mul_f32 v[166:167], v[176:177], v[166:167]
	v_pk_mul_f32 v[132:133], v[176:177], v[132:133]
	v_cvt_pk_bf16_f32 v190, v162, v163
	v_cvt_pk_bf16_f32 v191, v132, v133
	v_pk_mul_f32 v[132:133], v[54:55], v[54:55]
	v_pk_mul_f32 v[162:163], v[52:53], v[52:53]
	v_pk_fma_f32 v[168:169], v[136:137], v[170:171], v[168:169]
	v_cvt_pk_bf16_f32 v192, v166, v167
	v_pk_mov_b32 v[166:167], v[162:163], v[132:133] op_sel:[1,0]
	v_mov_b32_e32 v163, v133
	v_pk_mul_f32 v[168:169], v[176:177], v[168:169]
	v_pk_add_f32 v[132:133], v[166:167], v[162:163]
	v_pk_mul_f32 v[162:163], v[50:51], v[50:51]
	v_pk_mul_f32 v[166:167], v[48:49], v[48:49]
	v_cvt_pk_bf16_f32 v193, v168, v169
	v_mov_b32_e32 v168, v162
	v_mov_b32_e32 v169, v166
	v_mov_b32_e32 v166, v163
	global_store_dwordx4 v[164:165], v[190:193], off
	v_pk_add_f32 v[162:163], v[168:169], v[166:167]
	v_add_f32_e32 v129, v132, v133
	v_mbcnt_lo_u32_b32 v132, -1, 0
	v_mbcnt_hi_u32_b32 v132, -1, v132
	v_add_f32_e32 v129, v129, v163
	v_lshlrev_b32_e32 v132, 2, v132
	v_add_f32_e32 v129, v162, v129
	v_xor_b32_e32 v132, 64, v132
	ds_bpermute_b32 v132, v132, v129
	s_and_b64 vcc, exec, s[0:1]
	v_mov_b32_e32 v179, 1.0
	s_waitcnt lgkmcnt(0)
	v_add_f32_e32 v129, v129, v132
	v_mbcnt_lo_u32_b32 v132, -1, 0
	v_mbcnt_hi_u32_b32 v132, -1, v132
	s_nop 0
	v_lshlrev_b32_e32 v132, 2, v132
	v_xor_b32_e32 v132, 0x80, v132
	ds_bpermute_b32 v132, v132, v129
	s_waitcnt lgkmcnt(0)
	v_add_f32_e32 v129, v129, v132
	v_fmamk_f32 v129, v129, 0x3d000000, v208
	v_rsq_f32_e32 v132, v129
	v_mov_b32_e32 v129, 0
	v_pk_mul_f32 v[162:163], v[54:55], v[132:133] op_sel_hi:[1,0]
	v_pk_mul_f32 v[166:167], v[52:53], v[132:133] op_sel_hi:[1,0]
	v_pk_mul_f32 v[168:169], v[50:51], v[132:133] op_sel_hi:[1,0]
	v_pk_mul_f32 v[132:133], v[48:49], v[132:133] op_sel_hi:[1,0]
	v_mov_b32_e32 v170, v166
	v_mov_b32_e32 v171, v133
	v_mov_b32_e32 v133, v167
	v_pk_mul_f32 v[170:171], v[174:175], v[170:171]
	v_pk_mul_f32 v[132:133], v[158:159], v[132:133]
	v_mov_b32_e32 v166, v170
	v_pk_mul_f32 v[134:135], v[134:135], v[132:133]
	v_mov_b32_e32 v167, v133
	v_mov_b32_e32 v133, v171
	v_pk_mul_f32 v[132:133], v[194:195], v[132:133]
	v_pk_fma_f32 v[134:135], v[180:181], v[170:171], v[134:135]
	v_pk_fma_f32 v[132:133], v[172:173], v[166:167], v[132:133] neg_lo:[0,0,1] neg_hi:[0,0,1]
	v_mov_b32_e32 v167, v169
	v_mov_b32_e32 v169, v163
	v_mov_b32_e32 v166, v162
	v_pk_mul_f32 v[162:163], v[154:155], v[168:169]
	v_pk_mul_f32 v[166:167], v[156:157], v[166:167]
	v_pk_mul_f32 v[130:131], v[130:131], v[162:163]
	v_pk_mul_f32 v[134:135], v[176:177], v[134:135]
	v_pk_fma_f32 v[130:131], v[136:137], v[166:167], v[130:131]
	v_pk_mul_f32 v[132:133], v[176:177], v[132:133]
	v_pk_mul_f32 v[136:137], v[176:177], v[130:131]
	v_mov_b32_e32 v131, v163
	v_mov_b32_e32 v163, v167
	v_mov_b32_e32 v130, v166
	v_pk_mul_f32 v[162:163], v[198:199], v[162:163]
	s_nop 0
	v_pk_fma_f32 v[130:131], v[196:197], v[130:131], v[162:163] neg_lo:[0,0,1] neg_hi:[0,0,1]
	s_nop 0
	v_pk_mul_f32 v[162:163], v[176:177], v[130:131]
	v_cvt_pk_bf16_f32 v130, v132, v133
	v_cvt_pk_bf16_f32 v131, v162, v163
	v_cvt_pk_bf16_f32 v132, v134, v135
	v_cvt_pk_bf16_f32 v133, v136, v137
	global_store_dwordx4 v[164:165], v[130:133], off offset:64
	v_add_u32_e32 v136, 0x90, v184
	s_nop 0
	v_mov_b32_e32 v132, 1.0
	v_mov_b32_e32 v130, 0
	v_mov_b32_e32 v131, 1.0
	v_mov_b32_e32 v133, 0
	s_cbranch_vccnz .LBB0_262
	v_bfe_u32 v128, v136, 6, 7
	v_cndmask_b32_e64 v128, v186, v128, s[42:43]
	v_cvt_f32_u32_e32 v134, v128
	v_lshrrev_b32_e32 v135, 5, v153
	v_sub_u32_e32 v135, 0, v135
	v_and_b32_e32 v135, 0x35c28f6, v135
	v_sub_u32_e32 v135, 0x3f800000, v135
	v_mul_f32_e32 v134, v134, v135
	v_mul_f32_e32 v129, 0x3e22f983, v134
	v_cos_f32_e32 v128, v129
	v_sin_f32_e32 v129, v129
	v_mul_f32_e32 v131, 0x3d4e2601, v134
	v_cos_f32_e32 v130, v131
	v_sin_f32_e32 v131, v131
	v_mul_f32_e32 v133, 0x3c826136, v134
	v_cos_f32_e32 v132, v133
	v_sin_f32_e32 v133, v133
	v_mul_f32_e32 v135, 0x3ba4eb34, v134
	v_cos_f32_e32 v134, v135
	v_sin_f32_e32 v135, v135
	s_nop 0
	v_mov_b32_e32 v178, v129
	v_mov_b32_e32 v179, v130
	v_mov_b32_e32 v129, v131
	v_mov_b32_e32 v130, v133
	v_mov_b32_e32 v131, v134
	v_mov_b32_e32 v133, v135
.LBB0_262:
	v_pk_mul_f32 v[134:135], v[46:47], v[46:47]
	v_pk_mul_f32 v[162:163], v[44:45], v[44:45]
	v_readlane_b32 s22, v252, 52
	v_pk_mov_b32 v[164:165], v[162:163], v[134:135] op_sel:[1,0]
	v_mov_b32_e32 v163, v135
	v_pk_add_f32 v[134:135], v[164:165], v[162:163]
	v_pk_mul_f32 v[162:163], v[42:43], v[42:43]
	v_pk_mul_f32 v[164:165], v[40:41], v[40:41]
	v_mov_b32_e32 v166, v162
	v_mov_b32_e32 v167, v164
	v_mov_b32_e32 v164, v163
	v_pk_add_f32 v[162:163], v[166:167], v[164:165]
	v_add_f32_e32 v134, v134, v135
	v_mbcnt_lo_u32_b32 v135, -1, 0
	v_mbcnt_hi_u32_b32 v135, -1, v135
	v_add_f32_e32 v134, v134, v163
	v_lshlrev_b32_e32 v135, 2, v135
	v_add_f32_e32 v134, v162, v134
	v_xor_b32_e32 v135, 64, v135
	ds_bpermute_b32 v135, v135, v134
	v_readlane_b32 s23, v252, 53
	v_mov_b32_e32 v180, v178
	v_mov_b32_e32 v181, v129
	v_mov_b32_e32 v170, v128
	s_waitcnt lgkmcnt(0)
	v_add_f32_e32 v137, v134, v135
	v_mbcnt_lo_u32_b32 v134, -1, 0
	v_mbcnt_hi_u32_b32 v134, -1, v134
	v_mov_b32_e32 v171, v179
	v_lshlrev_b32_e32 v134, 2, v134
	v_xor_b32_e32 v134, 0x80, v134
	ds_bpermute_b32 v162, v134, v137
	v_mov_b64_e32 v[134:135], s[22:23]
	v_mad_i64_i32 v[134:135], s[22:23], v136, s71, v[134:135]
	v_lshl_add_u64 v[164:165], v[150:151], 1, v[134:135]
	s_waitcnt lgkmcnt(0)
	v_add_f32_e32 v137, v137, v162
	v_fmamk_f32 v137, v137, 0x3d000000, v208
	v_rsq_f32_e32 v162, v137
	v_mov_b32_e32 v192, v130
	v_mov_b32_e32 v193, v133
	s_and_b64 vcc, exec, s[0:1]
	v_pk_mul_f32 v[134:135], v[46:47], v[162:163] op_sel_hi:[1,0]
	v_pk_mul_f32 v[136:137], v[44:45], v[162:163] op_sel_hi:[1,0]
	v_pk_mul_f32 v[166:167], v[42:43], v[162:163] op_sel_hi:[1,0]
	v_pk_mul_f32 v[162:163], v[40:41], v[162:163] op_sel_hi:[1,0]
	v_mov_b32_e32 v168, v136
	v_mov_b32_e32 v169, v163
	v_mov_b32_e32 v163, v137
	v_pk_mul_f32 v[136:137], v[158:159], v[162:163]
	v_pk_mul_f32 v[168:169], v[174:175], v[168:169]
	v_pk_mul_f32 v[162:163], v[128:129], v[136:137]
	v_mov_b32_e32 v172, v168
	v_pk_fma_f32 v[162:163], v[178:179], v[168:169], v[162:163]
	v_mov_b32_e32 v173, v137
	v_mov_b32_e32 v137, v169
	v_mov_b32_e32 v168, v134
	v_mov_b32_e32 v169, v167
	v_mov_b32_e32 v167, v135
	v_pk_mul_f32 v[168:169], v[156:157], v[168:169]
	v_pk_mul_f32 v[134:135], v[154:155], v[166:167]
	v_pk_mul_f32 v[136:137], v[180:181], v[136:137]
	v_pk_mul_f32 v[166:167], v[132:133], v[134:135]
	v_mov_b32_e32 v191, v135
	v_mov_b32_e32 v135, v169
	v_pk_fma_f32 v[136:137], v[170:171], v[172:173], v[136:137] neg_lo:[0,0,1] neg_hi:[0,0,1]
	v_mov_b32_e32 v172, v132
	v_mov_b32_e32 v173, v131
	v_mov_b32_e32 v190, v168
	v_pk_mul_f32 v[134:135], v[192:193], v[134:135]
	v_pk_fma_f32 v[166:167], v[130:131], v[168:169], v[166:167]
	v_pk_fma_f32 v[134:135], v[172:173], v[190:191], v[134:135] neg_lo:[0,0,1] neg_hi:[0,0,1]
	v_pk_mul_f32 v[162:163], v[176:177], v[162:163]
	v_pk_mul_f32 v[136:137], v[176:177], v[136:137]
	v_pk_mul_f32 v[166:167], v[176:177], v[166:167]
	v_pk_mul_f32 v[168:169], v[176:177], v[134:135]
	v_cvt_pk_bf16_f32 v134, v136, v137
	v_cvt_pk_bf16_f32 v135, v168, v169
	v_cvt_pk_bf16_f32 v136, v162, v163
	v_cvt_pk_bf16_f32 v137, v166, v167
	global_store_dwordx4 v[164:165], v[134:137], off
	s_nop 1
	v_pk_mul_f32 v[134:135], v[38:39], v[38:39]
	v_pk_mul_f32 v[136:137], v[36:37], v[36:37]
	s_nop 0
	v_pk_mov_b32 v[162:163], v[136:137], v[134:135] op_sel:[1,0]
	v_mov_b32_e32 v137, v135
	v_pk_add_f32 v[134:135], v[162:163], v[136:137]
	v_pk_mul_f32 v[136:137], v[34:35], v[34:35]
	v_pk_mul_f32 v[162:163], v[32:33], v[32:33]
	v_mov_b32_e32 v166, v136
	v_mov_b32_e32 v167, v162
	v_mov_b32_e32 v162, v137
	v_pk_add_f32 v[136:137], v[166:167], v[162:163]
	v_add_f32_e32 v134, v134, v135
	v_mbcnt_lo_u32_b32 v135, -1, 0
	v_mbcnt_hi_u32_b32 v135, -1, v135
	v_add_f32_e32 v134, v134, v137
	v_lshlrev_b32_e32 v135, 2, v135
	v_add_f32_e32 v134, v136, v134
	v_xor_b32_e32 v135, 64, v135
	ds_bpermute_b32 v135, v135, v134
	s_waitcnt lgkmcnt(0)
	v_add_f32_e32 v134, v134, v135
	v_mbcnt_lo_u32_b32 v135, -1, 0
	v_mbcnt_hi_u32_b32 v135, -1, v135
	s_nop 0
	v_lshlrev_b32_e32 v135, 2, v135
	v_xor_b32_e32 v135, 0x80, v135
	ds_bpermute_b32 v135, v135, v134
	s_waitcnt lgkmcnt(0)
	v_add_f32_e32 v134, v134, v135
	v_fmamk_f32 v134, v134, 0x3d000000, v208
	v_rsq_f32_e32 v134, v134
	s_nop 0
	v_pk_mul_f32 v[136:137], v[38:39], v[134:135] op_sel_hi:[1,0]
	v_pk_mul_f32 v[162:163], v[36:37], v[134:135] op_sel_hi:[1,0]
	v_pk_mul_f32 v[166:167], v[34:35], v[134:135] op_sel_hi:[1,0]
	v_pk_mul_f32 v[134:135], v[32:33], v[134:135] op_sel_hi:[1,0]
	v_mov_b32_e32 v168, v162
	v_mov_b32_e32 v169, v135
	v_mov_b32_e32 v135, v163
	v_pk_mul_f32 v[134:135], v[158:159], v[134:135]
	v_pk_mul_f32 v[168:169], v[174:175], v[168:169]
	v_pk_mul_f32 v[128:129], v[128:129], v[134:135]
	s_nop 0
	v_pk_fma_f32 v[128:129], v[178:179], v[168:169], v[128:129]
	v_mov_b32_e32 v178, 0
	v_pk_mul_f32 v[162:163], v[176:177], v[128:129]
	v_mov_b32_e32 v129, v135
	v_mov_b32_e32 v135, v169
	v_mov_b32_e32 v128, v168
	v_pk_mul_f32 v[134:135], v[180:181], v[134:135]
	v_mov_b32_e32 v180, 0
	v_pk_fma_f32 v[128:129], v[170:171], v[128:129], v[134:135] neg_lo:[0,0,1] neg_hi:[0,0,1]
	v_mov_b32_e32 v135, v167
	v_mov_b32_e32 v167, v137
	v_mov_b32_e32 v134, v136
	v_pk_mul_f32 v[136:137], v[154:155], v[166:167]
	v_pk_mul_f32 v[134:135], v[156:157], v[134:135]
	v_pk_mul_f32 v[132:133], v[132:133], v[136:137]
	v_pk_mul_f32 v[128:129], v[176:177], v[128:129]
	v_pk_fma_f32 v[130:131], v[130:131], v[134:135], v[132:133]
	v_cvt_pk_bf16_f32 v128, v128, v129
	v_pk_mul_f32 v[132:133], v[176:177], v[130:131]
	v_mov_b32_e32 v131, v137
	v_mov_b32_e32 v137, v135
	v_mov_b32_e32 v130, v134
	v_pk_mul_f32 v[134:135], v[192:193], v[136:137]
	v_mov_b32_e32 v181, 1.0
	v_pk_fma_f32 v[130:131], v[172:173], v[130:131], v[134:135] neg_lo:[0,0,1] neg_hi:[0,0,1]
	v_mov_b32_e32 v134, 1.0
	v_pk_mul_f32 v[130:131], v[176:177], v[130:131]
	v_mov_b32_e32 v135, 0
	v_cvt_pk_bf16_f32 v129, v130, v131
	v_cvt_pk_bf16_f32 v130, v162, v163
	v_cvt_pk_bf16_f32 v131, v132, v133
	global_store_dwordx4 v[164:165], v[128:131], off offset:64
	v_mov_b32_e32 v136, 0
	v_mov_b32_e32 v137, 1.0
	v_add_u32_e32 v129, 0xa0, v184
	v_mov_b32_e32 v128, 1.0
	v_mov_b32_e32 v130, 1.0
	v_mov_b32_e32 v131, 0
	s_cbranch_vccnz .LBB0_264
	v_bfe_u32 v130, v129, 6, 7
	v_cndmask_b32_e64 v130, v187, v130, s[42:43]
	v_cvt_f32_u32_e32 v132, v130
	v_lshrrev_b32_e32 v133, 5, v153
	v_sub_u32_e32 v133, 0, v133
	v_and_b32_e32 v133, 0x35c28f6, v133
	v_sub_u32_e32 v133, 0x3f800000, v133
	v_mul_f32_e32 v132, v132, v133
	v_mul_f32_e32 v135, 0x3e22f983, v132
	v_cos_f32_e32 v134, v135
	v_sin_f32_e32 v135, v135
	v_mul_f32_e32 v137, 0x3d4e2601, v132
	v_cos_f32_e32 v136, v137
	v_sin_f32_e32 v137, v137
	v_mul_f32_e32 v131, 0x3c826136, v132
	v_cos_f32_e32 v130, v131
	v_sin_f32_e32 v131, v131
	v_mul_f32_e32 v133, 0x3ba4eb34, v132
	v_cos_f32_e32 v132, v133
	v_sin_f32_e32 v133, v133
	s_nop 0
	v_mov_b32_e32 v180, v135
	v_mov_b32_e32 v181, v136
	v_mov_b32_e32 v135, v137
	v_mov_b32_e32 v136, v131
	v_mov_b32_e32 v137, v132
	v_mov_b32_e32 v131, v133
.LBB0_264:
	v_pk_mul_f32 v[132:133], v[30:31], v[30:31]
	v_pk_mul_f32 v[162:163], v[28:29], v[28:29]
	v_readlane_b32 s22, v252, 52
	v_pk_mov_b32 v[164:165], v[162:163], v[132:133] op_sel:[1,0]
	v_mov_b32_e32 v163, v133
	v_pk_add_f32 v[132:133], v[164:165], v[162:163]
	v_pk_mul_f32 v[162:163], v[26:27], v[26:27]
	v_pk_mul_f32 v[164:165], v[24:25], v[24:25]
	v_mov_b32_e32 v166, v162
	v_mov_b32_e32 v167, v164
	v_mov_b32_e32 v164, v163
	v_pk_add_f32 v[162:163], v[166:167], v[164:165]
	v_add_f32_e32 v132, v132, v133
	v_mbcnt_lo_u32_b32 v133, -1, 0
	v_mbcnt_hi_u32_b32 v133, -1, v133
	v_add_f32_e32 v132, v132, v163
	v_lshlrev_b32_e32 v133, 2, v133
	v_add_f32_e32 v132, v162, v132
	v_xor_b32_e32 v133, 64, v133
	ds_bpermute_b32 v133, v133, v132
	v_readlane_b32 s23, v252, 53
	v_mov_b32_e32 v194, v180
	v_mov_b32_e32 v195, v135
	v_mov_b32_e32 v172, v134
	s_waitcnt lgkmcnt(0)
	v_add_f32_e32 v162, v132, v133
	v_mbcnt_lo_u32_b32 v132, -1, 0
	v_mbcnt_hi_u32_b32 v132, -1, v132
	v_mov_b32_e32 v173, v181
	v_lshlrev_b32_e32 v132, 2, v132
	v_xor_b32_e32 v132, 0x80, v132
	ds_bpermute_b32 v163, v132, v162
	v_mov_b64_e32 v[132:133], s[22:23]
	v_mad_i64_i32 v[132:133], s[22:23], v129, s71, v[132:133]
	v_lshl_add_u64 v[164:165], v[150:151], 1, v[132:133]
	s_waitcnt lgkmcnt(0)
	v_add_f32_e32 v162, v162, v163
	v_fmamk_f32 v162, v162, 0x3d000000, v208
	v_rsq_f32_e32 v162, v162
	v_mov_b32_e32 v196, v136
	v_mov_b32_e32 v197, v131
	s_and_b64 vcc, exec, s[0:1]
	v_pk_mul_f32 v[132:133], v[30:31], v[162:163] op_sel_hi:[1,0]
	v_pk_mul_f32 v[166:167], v[28:29], v[162:163] op_sel_hi:[1,0]
	v_pk_mul_f32 v[168:169], v[26:27], v[162:163] op_sel_hi:[1,0]
	v_pk_mul_f32 v[162:163], v[24:25], v[162:163] op_sel_hi:[1,0]
	v_mov_b32_e32 v170, v166
	v_mov_b32_e32 v171, v163
	v_mov_b32_e32 v163, v167
	v_pk_mul_f32 v[162:163], v[158:159], v[162:163]
	v_pk_mul_f32 v[170:171], v[174:175], v[170:171]
	v_pk_mul_f32 v[166:167], v[134:135], v[162:163]
	v_mov_b32_e32 v186, v170
	v_pk_fma_f32 v[166:167], v[180:181], v[170:171], v[166:167]
	v_mov_b32_e32 v187, v163
	v_mov_b32_e32 v163, v171
	v_mov_b32_e32 v170, v132
	v_mov_b32_e32 v171, v169
	v_mov_b32_e32 v169, v133
	v_pk_mul_f32 v[170:171], v[156:157], v[170:171]
	v_pk_mul_f32 v[132:133], v[154:155], v[168:169]
	v_pk_mul_f32 v[162:163], v[194:195], v[162:163]
	v_pk_mul_f32 v[168:169], v[130:131], v[132:133]
	v_mov_b32_e32 v191, v133
	v_mov_b32_e32 v133, v171
	v_pk_fma_f32 v[162:163], v[172:173], v[186:187], v[162:163] neg_lo:[0,0,1] neg_hi:[0,0,1]
	v_mov_b32_e32 v186, v130
	v_mov_b32_e32 v187, v137
	v_mov_b32_e32 v190, v170
	v_pk_mul_f32 v[132:133], v[196:197], v[132:133]
	v_pk_mul_f32 v[162:163], v[176:177], v[162:163]
	v_pk_fma_f32 v[132:133], v[186:187], v[190:191], v[132:133] neg_lo:[0,0,1] neg_hi:[0,0,1]
	v_pk_mul_f32 v[166:167], v[176:177], v[166:167]
	v_pk_mul_f32 v[132:133], v[176:177], v[132:133]
	v_cvt_pk_bf16_f32 v190, v162, v163
	v_cvt_pk_bf16_f32 v191, v132, v133
	v_pk_mul_f32 v[132:133], v[22:23], v[22:23]
	v_pk_mul_f32 v[162:163], v[20:21], v[20:21]
	v_pk_fma_f32 v[168:169], v[136:137], v[170:171], v[168:169]
	v_cvt_pk_bf16_f32 v192, v166, v167
	v_pk_mov_b32 v[166:167], v[162:163], v[132:133] op_sel:[1,0]
	v_mov_b32_e32 v163, v133
	v_pk_mul_f32 v[168:169], v[176:177], v[168:169]
	v_pk_add_f32 v[132:133], v[166:167], v[162:163]
	v_pk_mul_f32 v[162:163], v[18:19], v[18:19]
	v_pk_mul_f32 v[166:167], v[16:17], v[16:17]
	v_cvt_pk_bf16_f32 v193, v168, v169
	v_mov_b32_e32 v168, v162
	v_mov_b32_e32 v169, v166
	v_mov_b32_e32 v166, v163
	global_store_dwordx4 v[164:165], v[190:193], off
	v_pk_add_f32 v[162:163], v[168:169], v[166:167]
	v_add_f32_e32 v129, v132, v133
	v_mbcnt_lo_u32_b32 v132, -1, 0
	v_mbcnt_hi_u32_b32 v132, -1, v132
	v_add_f32_e32 v129, v129, v163
	v_lshlrev_b32_e32 v132, 2, v132
	v_add_f32_e32 v129, v162, v129
	v_xor_b32_e32 v132, 64, v132
	ds_bpermute_b32 v132, v132, v129
	v_mov_b32_e32 v179, 1.0
	s_waitcnt lgkmcnt(0)
	v_add_f32_e32 v129, v129, v132
	v_mbcnt_lo_u32_b32 v132, -1, 0
	v_mbcnt_hi_u32_b32 v132, -1, v132
	s_nop 0
	v_lshlrev_b32_e32 v132, 2, v132
	v_xor_b32_e32 v132, 0x80, v132
	ds_bpermute_b32 v132, v132, v129
	s_waitcnt lgkmcnt(0)
	v_add_f32_e32 v129, v129, v132
	v_fmamk_f32 v129, v129, 0x3d000000, v208
	v_rsq_f32_e32 v132, v129
	v_mov_b32_e32 v129, 0
	v_pk_mul_f32 v[162:163], v[22:23], v[132:133] op_sel_hi:[1,0]
	v_pk_mul_f32 v[166:167], v[20:21], v[132:133] op_sel_hi:[1,0]
	v_pk_mul_f32 v[168:169], v[18:19], v[132:133] op_sel_hi:[1,0]
	v_pk_mul_f32 v[132:133], v[16:17], v[132:133] op_sel_hi:[1,0]
	v_mov_b32_e32 v170, v166
	v_mov_b32_e32 v171, v133
	v_mov_b32_e32 v133, v167
	v_pk_mul_f32 v[170:171], v[174:175], v[170:171]
	v_pk_mul_f32 v[132:133], v[158:159], v[132:133]
	v_mov_b32_e32 v166, v170
	v_pk_mul_f32 v[134:135], v[134:135], v[132:133]
	v_mov_b32_e32 v167, v133
	v_mov_b32_e32 v133, v171
	v_pk_mul_f32 v[132:133], v[194:195], v[132:133]
	v_pk_fma_f32 v[134:135], v[180:181], v[170:171], v[134:135]
	v_pk_fma_f32 v[132:133], v[172:173], v[166:167], v[132:133] neg_lo:[0,0,1] neg_hi:[0,0,1]
	v_mov_b32_e32 v167, v169
	v_mov_b32_e32 v169, v163
	v_mov_b32_e32 v166, v162
	v_pk_mul_f32 v[162:163], v[154:155], v[168:169]
	v_pk_mul_f32 v[166:167], v[156:157], v[166:167]
	v_pk_mul_f32 v[130:131], v[130:131], v[162:163]
	v_pk_mul_f32 v[134:135], v[176:177], v[134:135]
	v_pk_fma_f32 v[130:131], v[136:137], v[166:167], v[130:131]
	v_pk_mul_f32 v[132:133], v[176:177], v[132:133]
	v_pk_mul_f32 v[136:137], v[176:177], v[130:131]
	v_mov_b32_e32 v131, v163
	v_mov_b32_e32 v163, v167
	v_mov_b32_e32 v130, v166
	v_pk_mul_f32 v[162:163], v[196:197], v[162:163]
	s_nop 0
	v_pk_fma_f32 v[130:131], v[186:187], v[130:131], v[162:163] neg_lo:[0,0,1] neg_hi:[0,0,1]
	s_nop 0
	v_pk_mul_f32 v[162:163], v[176:177], v[130:131]
	v_cvt_pk_bf16_f32 v130, v132, v133
	v_cvt_pk_bf16_f32 v131, v162, v163
	v_cvt_pk_bf16_f32 v132, v134, v135
	v_cvt_pk_bf16_f32 v133, v136, v137
	global_store_dwordx4 v[164:165], v[130:133], off offset:64
	v_add_u32_e32 v136, 0xb0, v184
	s_nop 0
	v_mov_b32_e32 v132, 1.0
	v_mov_b32_e32 v130, 0
	v_mov_b32_e32 v131, 1.0
	v_mov_b32_e32 v133, 0
	s_cbranch_vccnz .LBB0_266
	v_bfe_u32 v128, v136, 6, 7
	v_cndmask_b32_e64 v128, v188, v128, s[42:43]
	v_cvt_f32_u32_e32 v134, v128
	v_lshrrev_b32_e32 v135, 5, v153
	v_sub_u32_e32 v135, 0, v135
	v_and_b32_e32 v135, 0x35c28f6, v135
	v_sub_u32_e32 v135, 0x3f800000, v135
	v_mul_f32_e32 v134, v134, v135
	v_mul_f32_e32 v129, 0x3e22f983, v134
	v_cos_f32_e32 v128, v129
	v_sin_f32_e32 v129, v129
	v_mul_f32_e32 v131, 0x3d4e2601, v134
	v_cos_f32_e32 v130, v131
	v_sin_f32_e32 v131, v131
	v_mul_f32_e32 v133, 0x3c826136, v134
	v_cos_f32_e32 v132, v133
	v_sin_f32_e32 v133, v133
	v_mul_f32_e32 v135, 0x3ba4eb34, v134
	v_cos_f32_e32 v134, v135
	v_sin_f32_e32 v135, v135
	s_nop 0
	v_mov_b32_e32 v178, v129
	v_mov_b32_e32 v179, v130
	v_mov_b32_e32 v129, v131
	v_mov_b32_e32 v130, v133
	v_mov_b32_e32 v131, v134
	v_mov_b32_e32 v133, v135

.LBB0_849:
	s_or_b64 exec, exec, s[18:19]
	v_or_b32_e32 v64, 4, v184
	v_ashrrev_i32_e32 v65, 31, v64
	v_lshlrev_b64 v[76:77], 2, v[64:65]
	v_lshl_add_u64 v[64:65], s[28:29], 0, v[76:77]
	v_lshl_add_u64 v[66:67], s[30:31], 0, v[76:77]
	v_lshl_add_u64 v[72:73], s[34:35], 0, v[76:77]
	global_load_dwordx4 v[88:91], v[186:187], off offset:16
	global_load_dwordx4 v[92:95], v[64:65], off
	global_load_dwordx4 v[68:71], v[66:67], off
	s_nop 0
	global_load_dwordx4 v[64:67], v[188:189], off offset:16
	v_lshl_add_u64 v[74:75], s[36:37], 0, v[76:77]
	global_load_dwordx4 v[80:83], v[72:73], off
	global_load_dwordx4 v[84:87], v[74:75], off
	v_lshl_add_u64 v[72:73], s[40:41], 0, v[76:77]
	v_lshl_add_u64 v[76:77], s[42:43], 0, v[76:77]
	global_load_dwordx4 v[72:75], v[72:73], off
	global_load_dwordx4 v[76:79], v[76:77], off
	s_waitcnt vmcnt(0)
	v_mov_b32_dpp v110, v8 row_shr:1 row_mask:0xf bank_mask:0xf bound_ctrl:1
	v_mov_b32_dpp v102, v60 row_shl:1 row_mask:0xf bank_mask:0xf bound_ctrl:1
	v_mov_b32_dpp v108, v0 row_shr:1 row_mask:0xf bank_mask:0xf bound_ctrl:1
	v_mov_b32_dpp v100, v56 row_shl:1 row_mask:0xf bank_mask:0xf bound_ctrl:1
	v_mov_b32_dpp v111, v9 row_shr:1 row_mask:0xf bank_mask:0xf bound_ctrl:1
	v_mov_b32_dpp v103, v61 row_shl:1 row_mask:0xf bank_mask:0xf bound_ctrl:1
	v_mov_b32_dpp v109, v1 row_shr:1 row_mask:0xf bank_mask:0xf bound_ctrl:1
	v_mov_b32_dpp v101, v57 row_shl:1 row_mask:0xf bank_mask:0xf bound_ctrl:1
	v_mov_b32_dpp v106, v10 row_shr:1 row_mask:0xf bank_mask:0xf bound_ctrl:1
	v_mov_b32_dpp v98, v62 row_shl:1 row_mask:0xf bank_mask:0xf bound_ctrl:1
	v_mov_b32_dpp v104, v2 row_shr:1 row_mask:0xf bank_mask:0xf bound_ctrl:1
	v_mov_b32_dpp v96, v58 row_shl:1 row_mask:0xf bank_mask:0xf bound_ctrl:1
	v_mov_b32_dpp v107, v11 row_shr:1 row_mask:0xf bank_mask:0xf bound_ctrl:1
	v_mov_b32_dpp v99, v63 row_shl:1 row_mask:0xf bank_mask:0xf bound_ctrl:1
	v_mov_b32_dpp v105, v3 row_shr:1 row_mask:0xf bank_mask:0xf bound_ctrl:1
	v_mov_b32_dpp v97, v59 row_shl:1 row_mask:0xf bank_mask:0xf bound_ctrl:1
	s_waitcnt vmcnt(0)
	s_and_saveexec_b64 s[18:19], s[50:51]
	s_cbranch_execnz .LBB0_858
	s_or_b64 exec, exec, s[18:19]
	s_and_saveexec_b64 s[18:19], s[52:53]
	s_cbranch_execnz .LBB0_859
